# fused final epilogue: the 16 per-row partial sums are read with four 16-byte loads instead of sixteen 4-byte loads (same summation order)
# speedup vs baseline: 1.0035x; 1.0035x over previous
; __device__ __forceinline__ void epi_final(f32x4 (&acc)[2][2][4][2], const Unit& u, int wr, int wc, int fr, int fq, const EpiArgs& E, LAS float* rt) {
;     ...
;     if (tid < 256) { const unsigned* sp = (const unsigned*)E.stOut + (size_t)(u.pm * BM + tid) * 16; float s = 0.f;
; #pragma unroll
;         for (int j = 0; j < 16; ++j) s += __uint_as_float(__hip_atomic_load(sp + j, __ATOMIC_RELAXED, __HIP_MEMORY_SCOPE_AGENT));
;         rt[tid] = rsqrtf(s * (1.0f / 1024.0f) + EPS); }
.LBB0_1439:
	s_movk_i32 s0, 0x100
	v_cmp_gt_u32_e32 vcc, s0, v0
	s_waitcnt lgkmcnt(0)
	s_barrier
	s_and_saveexec_b64 s[0:1], vcc
	s_cbranch_execz .LBB0_1441
	v_or_b32_e32 v148, s8, v0
	v_ashrrev_i32_e32 v149, 31, v148
	v_lshlrev_b64 v[148:149], 6, v[148:149]
	v_lshl_add_u64 v[148:149], s[10:11], 0, v[148:149]
	global_load_dwordx4 v[150:153], v[148:149], off sc1
	global_load_dwordx4 v[154:157], v[148:149], off offset:16 sc1
	global_load_dwordx4 v[158:161], v[148:149], off offset:32 sc1
	global_load_dwordx4 v[162:165], v[148:149], off offset:48 sc1
	v_mov_b32_e32 v149, 0x358637bd
	s_mov_b32 s4, 0x800000
	s_waitcnt vmcnt(3)
	v_add_f32_e32 v150, 0, v150
	v_add_f32_e32 v150, v150, v151
	v_add_f32_e32 v150, v150, v152
	v_add_f32_e32 v150, v150, v153
	s_waitcnt vmcnt(2)
	v_add_f32_e32 v150, v150, v154
	v_add_f32_e32 v150, v150, v155
	v_add_f32_e32 v150, v150, v156
	v_add_f32_e32 v150, v150, v157
	s_waitcnt vmcnt(1)
	v_add_f32_e32 v150, v150, v158
	v_add_f32_e32 v150, v150, v159
	v_add_f32_e32 v150, v150, v160
	v_add_f32_e32 v150, v150, v161
	s_waitcnt vmcnt(0)
	v_add_f32_e32 v150, v150, v162
	v_add_f32_e32 v150, v150, v163
	v_add_f32_e32 v150, v150, v164
	v_add_f32_e32 v148, v150, v165
	v_fmac_f32_e32 v149, 0x3a800000, v148
	v_mul_f32_e32 v148, 0x4b800000, v149
	v_cmp_gt_f32_e32 vcc, s4, v149
	s_nop 1
	v_cndmask_b32_e32 v148, v149, v148, vcc
	v_rsq_f32_e32 v148, v148
	v_lshl_add_u32 v149, v0, 2, 0
	v_add_u32_e32 v149, 0x20010, v149
	v_mul_f32_e32 v150, 0x45800000, v148
	v_cndmask_b32_e32 v148, v148, v150, vcc
	ds_write_b32 v149, v148
